# mixer output stores plain instead of nt on top of the out-proj plain residual loads
# speedup vs baseline: 1.0097x; 1.0097x over previous
; #define LAS __attribute__((address_space(3)))
; __device__ __forceinline__ void attn_sample_item(const Args& a, int l, int n, LAS unsigned char* lds, int tid, int lane, int wave) {
;     ...
; #pragma unroll
;     for (int pass = 0; pass < 4; ++pass) {
;         const int r = pass * 32 + (tid >> 4);
;         kc[pass][0] = __builtin_nontemporal_load((const f32x4*)(ck + r * 128 + c16 * 8)); kc[pass][1] = __builtin_nontemporal_load((const f32x4*)(ck + r * 128 + c16 * 8 + 4));
;         vc[pass][0] = __builtin_nontemporal_load((const f32x4*)(cv + r * 128 + c16 * 8)); vc[pass][1] = __builtin_nontemporal_load((const f32x4*)(cv + r * 128 + c16 * 8 + 4));
;     }
; #pragma unroll
;     for (int pass = 0; pass < 4; ++pass) {
;         const int r = pass * 32 + (tid >> 4);
;         const f32x4 k0 = kc[pass][0], k1 = kc[pass][1], v0 = vc[pass][0], v1 = vc[pass][1];
;         u32x4 kw; kw.x = pk_bf16(k0.x, k0.y); kw.y = pk_bf16(k0.z, k0.w); kw.z = pk_bf16(k1.x, k1.y); kw.w = pk_bf16(k1.z, k1.w);
;         u32x4 vw; vw.x = pk_bf16(v0.x, v0.y); vw.y = pk_bf16(v0.z, v0.w); vw.z = pk_bf16(v1.x, v1.y); vw.w = pk_bf16(v1.z, v1.w);
;         *(LAS u32x4*)(lds + kvh * KH + r * 144 + sub * 16) = kw;
;         *(LAS u32x4*)(lds + VOFF + kvh * 2 * VH + (sub >> 2) * VH + r * 64 + (sub & 3) * 16) = vw;
;         if (r >= 8) { float* pk = oks + (r - 8) * 128 + c16 * 8; float* pv = ovs + (r - 8) * 128 + c16 * 8;
;             __builtin_nontemporal_store(k0, (f32x4*)pk); __builtin_nontemporal_store(k1, (f32x4*)(pk + 4)); __builtin_nontemporal_store(v0, (f32x4*)pv); __builtin_nontemporal_store(v1, (f32x4*)(pv + 4)); }
.LBB0_506:
	v_readlane_b32 s0, v255, 23
	s_add_i32 s4, s36, s0
	s_ashr_i32 s5, s4, 31
	s_lshl_b64 s[18:19], s[4:5], 16
	v_readlane_b32 s0, v253, 4
	v_readlane_b32 s6, v253, 10
	v_readlane_b32 s10, v253, 14
	v_readlane_b32 s7, v253, 11
	v_readlane_b32 s11, v253, 15
	s_add_u32 s6, s10, s18
	v_readlane_b32 s8, v253, 12
	v_readlane_b32 s12, v253, 16
	s_addc_u32 s7, s11, s19
	v_lshlrev_b32_e32 v16, 3, v130
	v_readlane_b32 s9, v253, 13
	v_readlane_b32 s13, v253, 17
	s_add_u32 s8, s12, s18
	v_and_b32_e32 v97, 15, v130
	v_and_b32_e32 v16, 0xffffff80, v16
	s_addc_u32 s9, s13, s19
	v_lshlrev_b32_e32 v172, 5, v97
	v_ashrrev_i32_e32 v17, 31, v16
	v_lshl_add_u64 v[18:19], s[6:7], 0, v[172:173]
	v_lshl_add_u64 v[20:21], s[8:9], 0, v[172:173]
	v_lshlrev_b64 v[22:23], 2, v[16:17]
	v_lshl_add_u64 v[24:25], v[18:19], 0, v[22:23]
	v_lshl_add_u64 v[22:23], v[20:21], 0, v[22:23]
	global_load_dwordx4 v[64:67], v[24:25], off offset:16 nt
	global_load_dwordx4 v[72:75], v[24:25], off nt
	global_load_dwordx4 v[68:71], v[22:23], off offset:16 nt
	global_load_dwordx4 v[76:79], v[22:23], off nt
	v_add_u32_e32 v22, 0x1000, v16
	v_ashrrev_i32_e32 v23, 31, v22
	v_lshlrev_b64 v[22:23], 2, v[22:23]
	v_lshl_add_u64 v[24:25], v[18:19], 0, v[22:23]
	v_lshl_add_u64 v[22:23], v[20:21], 0, v[22:23]
	global_load_dwordx4 v[48:51], v[24:25], off offset:16 nt
	global_load_dwordx4 v[56:59], v[24:25], off nt
	global_load_dwordx4 v[52:55], v[22:23], off offset:16 nt
	global_load_dwordx4 v[60:63], v[22:23], off nt
	v_add_u32_e32 v22, 0x2000, v16
	v_ashrrev_i32_e32 v23, 31, v22
	v_lshlrev_b64 v[22:23], 2, v[22:23]
	v_add_u32_e32 v16, 0x3000, v16
	v_lshl_add_u64 v[24:25], v[18:19], 0, v[22:23]
	v_lshl_add_u64 v[22:23], v[20:21], 0, v[22:23]
	v_ashrrev_i32_e32 v17, 31, v16
	global_load_dwordx4 v[32:35], v[24:25], off offset:16 nt
	global_load_dwordx4 v[40:43], v[24:25], off nt
	global_load_dwordx4 v[36:39], v[22:23], off offset:16 nt
	global_load_dwordx4 v[44:47], v[22:23], off nt
	v_lshlrev_b64 v[22:23], 2, v[16:17]
	v_lshl_add_u64 v[24:25], v[18:19], 0, v[22:23]
	v_lshl_add_u64 v[28:29], v[20:21], 0, v[22:23]
	global_load_dwordx4 v[16:19], v[24:25], off offset:16 nt
	s_nop 0
	global_load_dwordx4 v[24:27], v[24:25], off nt
	s_nop 0
	global_load_dwordx4 v[20:23], v[28:29], off offset:16 nt
	s_nop 0
	global_load_dwordx4 v[28:31], v[28:29], off nt
	v_bfe_u32 v99, v130, 3, 1
	s_movk_i32 s6, 0x5a00
	v_readlane_b32 s0, v254, 18
	v_lshrrev_b32_e32 v101, 2, v107
	v_mad_u32_u24 v110, v99, s6, 0
	s_add_u32 s6, s0, s18
	v_readlane_b32 s0, v254, 19
	v_readlane_b32 s4, v253, 8
	v_ashrrev_i32_e32 v100, 4, v130
	v_lshlrev_b32_e32 v98, 4, v107
	v_lshlrev_b32_e32 v102, 4, v130
	v_mul_i32_i24_e32 v103, 0xfffff600, v99
	v_mul_u32_u24_e32 v104, 0x2800, v101
	s_addc_u32 s7, s0, s19
	v_readlane_b32 s0, v254, 20
	v_readlane_b32 s5, v253, 9
	v_and_b32_e32 v111, 48, v102
	v_mul_lo_u32 v114, v100, s84
	v_add_u32_e32 v101, v110, v98
	v_add3_u32 v112, v110, v103, v104
	s_add_u32 s4, s0, s18
	v_readlane_b32 s0, v254, 21
	v_add_u32_e32 v113, v112, v111
	v_add_u32_e32 v115, v101, v114
	s_addc_u32 s5, s0, s19
	v_lshl_add_u32 v120, v100, 6, v113
	v_lshl_add_u64 v[102:103], s[6:7], 0, v[172:173]
	v_lshl_add_u64 v[104:105], s[4:5], 0, v[172:173]
	v_cmp_lt_i32_e32 vcc, 7, v100
	v_readlane_b32 s1, v253, 5
	v_readlane_b32 s2, v253, 6
	v_readlane_b32 s3, v253, 7
	v_readlane_b32 s14, v253, 18
	v_readlane_b32 s15, v253, 19
	s_waitcnt vmcnt(15)
	v_cvt_pk_bf16_f32 v118, v64, v65
	s_waitcnt vmcnt(14)
	v_cvt_pk_bf16_f32 v116, v72, v73
	v_cvt_pk_bf16_f32 v117, v74, v75
	v_cvt_pk_bf16_f32 v119, v66, v67
	ds_write_b128 v115, v[116:119]
	s_waitcnt vmcnt(12)
	v_cvt_pk_bf16_f32 v116, v76, v77
	v_cvt_pk_bf16_f32 v117, v78, v79
	v_cvt_pk_bf16_f32 v118, v68, v69
	v_cvt_pk_bf16_f32 v119, v70, v71
	ds_write_b128 v120, v[116:119] offset:46080
	s_and_saveexec_b64 s[8:9], vcc
	s_cbranch_execz .LBB0_508
	v_lshl_add_u32 v172, v100, 7, v225
	v_lshlrev_b64 v[116:117], 2, v[172:173]
	v_lshl_add_u64 v[118:119], v[104:105], 0, v[116:117]
	v_lshl_add_u64 v[116:117], v[102:103], 0, v[116:117]
	global_store_dwordx4 v[116:117], v[72:75], off
	global_store_dwordx4 v[116:117], v[64:67], off offset:16
	global_store_dwordx4 v[118:119], v[76:79], off
	global_store_dwordx4 v[118:119], v[68:71], off offset:16
; #define LAS __attribute__((address_space(3)))
; __device__ __forceinline__ void attn_sample_item(const Args& a, int l, int n, LAS unsigned char* lds, int tid, int lane, int wave) {
;     ...
; #pragma unroll
;     for (int pass = 0; pass < 4; ++pass) {
;         const int r = pass * 32 + (tid >> 4);
;         const f32x4 k0 = kc[pass][0], k1 = kc[pass][1], v0 = vc[pass][0], v1 = vc[pass][1];
;         u32x4 kw; kw.x = pk_bf16(k0.x, k0.y); kw.y = pk_bf16(k0.z, k0.w); kw.z = pk_bf16(k1.x, k1.y); kw.w = pk_bf16(k1.z, k1.w);
;         u32x4 vw; vw.x = pk_bf16(v0.x, v0.y); vw.y = pk_bf16(v0.z, v0.w); vw.z = pk_bf16(v1.x, v1.y); vw.w = pk_bf16(v1.z, v1.w);
;         *(LAS u32x4*)(lds + kvh * KH + r * 144 + sub * 16) = kw;
;         *(LAS u32x4*)(lds + VOFF + kvh * 2 * VH + (sub >> 2) * VH + r * 64 + (sub & 3) * 16) = vw;
;         if (r >= 8) { float* pk = oks + (r - 8) * 128 + c16 * 8; float* pv = ovs + (r - 8) * 128 + c16 * 8;
;             __builtin_nontemporal_store(k0, (f32x4*)pk); __builtin_nontemporal_store(k1, (f32x4*)(pk + 4)); __builtin_nontemporal_store(v0, (f32x4*)pv); __builtin_nontemporal_store(v1, (f32x4*)(pv + 4)); }
.LBB0_508:
	s_or_b64 exec, exec, s[8:9]
	v_add_u32_e32 v64, 0x1200, v114
	v_add_u32_e32 v65, 32, v100
	s_waitcnt vmcnt(10)
	v_cvt_pk_bf16_f32 v66, v56, v57
	v_cvt_pk_bf16_f32 v67, v58, v59
	v_cvt_pk_bf16_f32 v68, v48, v49
	v_cvt_pk_bf16_f32 v69, v50, v51
	v_add_u32_e32 v74, v101, v64
	s_movk_i32 s8, 0xffe7
	s_waitcnt vmcnt(8)
	v_cvt_pk_bf16_f32 v70, v60, v61
	v_cvt_pk_bf16_f32 v71, v62, v63
	v_cvt_pk_bf16_f32 v72, v52, v53
	v_cvt_pk_bf16_f32 v73, v54, v55
	ds_write_b128 v74, v[66:69]
	v_lshl_add_u32 v66, v65, 6, v113
	v_cmp_lt_i32_e32 vcc, s8, v100
	ds_write_b128 v66, v[70:73] offset:46080
	s_and_saveexec_b64 s[8:9], vcc
	s_cbranch_execz .LBB0_510
	v_lshl_add_u32 v172, v65, 7, v225
	v_lshlrev_b64 v[66:67], 2, v[172:173]
	v_lshl_add_u64 v[68:69], v[104:105], 0, v[66:67]
	v_lshl_add_u64 v[66:67], v[102:103], 0, v[66:67]
	global_store_dwordx4 v[66:67], v[56:59], off
	global_store_dwordx4 v[66:67], v[48:51], off offset:16
	global_store_dwordx4 v[68:69], v[60:63], off
	global_store_dwordx4 v[68:69], v[52:55], off offset:16
.LBB0_510:
	s_or_b64 exec, exec, s[8:9]
	v_add_u32_e32 v48, 0x1200, v64
	v_add_u32_e32 v49, 64, v100
	s_waitcnt vmcnt(6)
	v_cvt_pk_bf16_f32 v50, v40, v41
	v_cvt_pk_bf16_f32 v51, v42, v43
	v_cvt_pk_bf16_f32 v52, v32, v33
	v_cvt_pk_bf16_f32 v53, v34, v35
	v_add_u32_e32 v58, v101, v48
	s_movk_i32 s8, 0xffc7
	s_waitcnt vmcnt(4)
	v_cvt_pk_bf16_f32 v54, v44, v45
	v_cvt_pk_bf16_f32 v55, v46, v47
	v_cvt_pk_bf16_f32 v56, v36, v37
	v_cvt_pk_bf16_f32 v57, v38, v39
	ds_write_b128 v58, v[50:53]
	v_lshl_add_u32 v50, v49, 6, v113
	v_cmp_lt_i32_e32 vcc, s8, v100
	ds_write_b128 v50, v[54:57] offset:46080
	s_and_saveexec_b64 s[8:9], vcc
	s_cbranch_execz .LBB0_512
	v_lshl_add_u32 v172, v49, 7, v225
	v_lshlrev_b64 v[50:51], 2, v[172:173]
	v_lshl_add_u64 v[52:53], v[104:105], 0, v[50:51]
	v_lshl_add_u64 v[50:51], v[102:103], 0, v[50:51]
	global_store_dwordx4 v[50:51], v[40:43], off
	global_store_dwordx4 v[50:51], v[32:35], off offset:16
	global_store_dwordx4 v[52:53], v[44:47], off
	global_store_dwordx4 v[52:53], v[36:39], off offset:16
.LBB0_512:
	s_or_b64 exec, exec, s[8:9]
	v_add_u32_e32 v32, 0x1200, v48
	v_add_u32_e32 v33, 0x60, v100
	s_waitcnt vmcnt(2)
	v_cvt_pk_bf16_f32 v34, v24, v25
	v_cvt_pk_bf16_f32 v35, v26, v27
	v_cvt_pk_bf16_f32 v36, v16, v17
	v_cvt_pk_bf16_f32 v37, v18, v19
	v_add_u32_e32 v42, v101, v32
	s_movk_i32 s8, 0xffa7
	s_waitcnt vmcnt(0)
	v_cvt_pk_bf16_f32 v38, v28, v29
	v_cvt_pk_bf16_f32 v39, v30, v31
	v_cvt_pk_bf16_f32 v40, v20, v21
	v_cvt_pk_bf16_f32 v41, v22, v23
	ds_write_b128 v42, v[34:37]
	v_lshl_add_u32 v34, v33, 6, v113
	v_cmp_lt_i32_e32 vcc, s8, v100
	ds_write_b128 v34, v[38:41] offset:46080
	s_and_saveexec_b64 s[8:9], vcc
	s_cbranch_execz .LBB0_517
	v_lshl_add_u32 v172, v33, 7, v225
	v_lshlrev_b64 v[34:35], 2, v[172:173]
	v_lshl_add_u64 v[36:37], v[104:105], 0, v[34:35]
	v_lshl_add_u64 v[34:35], v[102:103], 0, v[34:35]
	global_store_dwordx4 v[34:35], v[24:27], off
	global_store_dwordx4 v[34:35], v[16:19], off offset:16
	global_store_dwordx4 v[36:37], v[28:31], off
	global_store_dwordx4 v[36:37], v[20:23], off offset:16
	s_or_b64 exec, exec, s[8:9]
	s_and_b64 vcc, exec, s[16:17]
	s_cbranch_vccz .LBB0_518
